# GEMM epilogues: packed f32 ops split into scalar pairs, redundant canonicalising max removed in FF1 epilogue
# baseline (speedup 1.0000x reference)
.LBB0_78:
	s_waitcnt vmcnt(0)
	v_cvt_f32_f16_sdwa v189, v166 dst_sel:DWORD dst_unused:UNUSED_PAD src0_sel:WORD_1
	v_cvt_f32_f16_sdwa v191, v168 dst_sel:DWORD dst_unused:UNUSED_PAD src0_sel:WORD_1
	v_cvt_f32_f16_sdwa v193, v169 dst_sel:DWORD dst_unused:UNUSED_PAD src0_sel:WORD_1
	v_cvt_f32_f16_sdwa v199, v167 dst_sel:DWORD dst_unused:UNUSED_PAD src0_sel:WORD_1
	v_cvt_f32_f16_e32 v198, v167
	v_cvt_f32_f16_e32 v192, v169
	v_cvt_f32_f16_e32 v190, v168
	v_cvt_f32_f16_e32 v188, v166
	v_fma_f32 v140, v140, v152, v198
	v_fma_f32 v141, v141, v153, v199
	v_fma_f32 v136, v136, v148, v192
	v_fma_f32 v137, v137, v149, v193
	v_fma_f32 v166, v134, v146, v190
	v_fma_f32 v167, v135, v147, v191
	v_fma_f32 v138, v138, v150, v188
	v_fma_f32 v139, v139, v151, v189
	v_cvt_pk_f16_f32 v137, v136, v137
	v_cvt_pk_f16_f32 v135, v140, v141
	v_cvt_pk_f16_f32 v136, v166, v167
	v_cvt_pk_f16_f32 v134, v138, v139
	global_store_dwordx4 v[186:187], v[134:137], off
	v_cvt_f32_f16_sdwa v139, v164 dst_sel:DWORD dst_unused:UNUSED_PAD src0_sel:WORD_1
	v_cvt_f32_f16_sdwa v141, v165 dst_sel:DWORD dst_unused:UNUSED_PAD src0_sel:WORD_1
	v_cvt_f32_f16_sdwa v137, v162 dst_sel:DWORD dst_unused:UNUSED_PAD src0_sel:WORD_1
	v_cvt_f32_f16_e32 v136, v162
	v_cvt_f32_f16_sdwa v167, v163 dst_sel:DWORD dst_unused:UNUSED_PAD src0_sel:WORD_1
	v_cvt_f32_f16_e32 v166, v163
	v_cvt_f32_f16_e32 v140, v165
	v_cvt_f32_f16_e32 v138, v164
	v_add_u32_e32 v134, 16, v170
	v_fma_f32 v122, v122, v150, v136
	v_fma_f32 v123, v123, v151, v137
	v_ashrrev_i32_e32 v135, 31, v134
	v_fma_f32 v124, v124, v152, v166
	v_fma_f32 v125, v125, v153, v167
	v_fma_f32 v120, v120, v148, v140
	v_fma_f32 v121, v121, v149, v141
	v_fma_f32 v138, v118, v146, v138
	v_fma_f32 v139, v119, v147, v139
	v_cvt_pk_f16_f32 v118, v122, v123
	v_lshlrev_b64 v[122:123], 11, v[134:135]
	v_cvt_pk_f16_f32 v121, v120, v121
	v_cvt_pk_f16_f32 v119, v124, v125
	v_cvt_pk_f16_f32 v120, v138, v139
	v_lshl_add_u64 v[122:123], v[178:179], 0, v[122:123]
	global_store_dwordx4 v[122:123], v[118:121], off
	v_cvt_f32_f16_sdwa v123, v160 dst_sel:DWORD dst_unused:UNUSED_PAD src0_sel:WORD_1
	v_cvt_f32_f16_sdwa v125, v161 dst_sel:DWORD dst_unused:UNUSED_PAD src0_sel:WORD_1
	v_cvt_f32_f16_sdwa v121, v158 dst_sel:DWORD dst_unused:UNUSED_PAD src0_sel:WORD_1
	v_cvt_f32_f16_e32 v120, v158
	v_cvt_f32_f16_sdwa v135, v159 dst_sel:DWORD dst_unused:UNUSED_PAD src0_sel:WORD_1
	v_cvt_f32_f16_e32 v134, v159
	v_cvt_f32_f16_e32 v124, v161
	v_cvt_f32_f16_e32 v122, v160
	v_add_u32_e32 v118, 32, v170
	v_fma_f32 v110, v110, v150, v120
	v_fma_f32 v111, v111, v151, v121
	v_ashrrev_i32_e32 v119, 31, v118
	v_fma_f32 v112, v112, v152, v134
	v_fma_f32 v113, v113, v153, v135
	v_fma_f32 v108, v108, v148, v124
	v_fma_f32 v109, v109, v149, v125
	v_fma_f32 v122, v106, v146, v122
	v_fma_f32 v123, v107, v147, v123
	v_cvt_pk_f16_f32 v106, v110, v111
	v_lshlrev_b64 v[110:111], 11, v[118:119]
	v_cvt_pk_f16_f32 v109, v108, v109
	v_cvt_pk_f16_f32 v107, v112, v113
	v_cvt_pk_f16_f32 v108, v122, v123
	v_lshl_add_u64 v[110:111], v[178:179], 0, v[110:111]
	global_store_dwordx4 v[110:111], v[106:109], off
	v_cvt_f32_f16_sdwa v111, v156 dst_sel:DWORD dst_unused:UNUSED_PAD src0_sel:WORD_1
	v_cvt_f32_f16_sdwa v113, v157 dst_sel:DWORD dst_unused:UNUSED_PAD src0_sel:WORD_1
	v_cvt_f32_f16_sdwa v109, v154 dst_sel:DWORD dst_unused:UNUSED_PAD src0_sel:WORD_1
	v_cvt_f32_f16_e32 v108, v154
	v_cvt_f32_f16_sdwa v119, v155 dst_sel:DWORD dst_unused:UNUSED_PAD src0_sel:WORD_1
	v_cvt_f32_f16_e32 v118, v155
	v_cvt_f32_f16_e32 v112, v157
	v_cvt_f32_f16_e32 v110, v156
	v_add_u32_e32 v106, 48, v170
	v_fma_f32 v102, v102, v150, v108
	v_fma_f32 v103, v103, v151, v109
	v_ashrrev_i32_e32 v107, 31, v106
	v_fma_f32 v104, v104, v152, v118
	v_fma_f32 v105, v105, v153, v119
	v_fma_f32 v100, v100, v148, v112
	v_fma_f32 v101, v101, v149, v113
	v_fma_f32 v110, v98, v146, v110
	v_fma_f32 v111, v99, v147, v111
	v_cvt_pk_f16_f32 v98, v102, v103
	v_lshlrev_b64 v[102:103], 11, v[106:107]
	v_cvt_pk_f16_f32 v101, v100, v101
	v_cvt_pk_f16_f32 v99, v104, v105
	v_cvt_pk_f16_f32 v100, v110, v111
	v_lshl_add_u64 v[102:103], v[178:179], 0, v[102:103]
	global_store_dwordx4 v[102:103], v[98:101], off
	s_and_b64 vcc, exec, s[36:37]
	s_nop 0
	v_add_u32_e32 v98, 0x80, v80
	s_cbranch_vccnz .LBB0_80
	v_cvt_f32_f16_sdwa v103, v142 dst_sel:DWORD dst_unused:UNUSED_PAD src0_sel:WORD_1
	v_cvt_f32_f16_e32 v102, v142
	v_cvt_f32_f16_sdwa v101, v144 dst_sel:DWORD dst_unused:UNUSED_PAD src0_sel:WORD_1
	v_cvt_f32_f16_sdwa v105, v145 dst_sel:DWORD dst_unused:UNUSED_PAD src0_sel:WORD_1
	v_cvt_f32_f16_sdwa v107, v143 dst_sel:DWORD dst_unused:UNUSED_PAD src0_sel:WORD_1
	v_cvt_f32_f16_e32 v106, v143
	v_cvt_f32_f16_e32 v104, v145
	v_cvt_f32_f16_e32 v100, v144
	v_fma_f32 v94, v94, v150, v102
	v_fma_f32 v95, v95, v151, v103
	v_ashrrev_i32_e32 v99, 31, v98
	v_fma_f32 v96, v96, v152, v106
	v_fma_f32 v97, v97, v153, v107
	v_fma_f32 v92, v92, v148, v104
	v_fma_f32 v93, v93, v149, v105
	v_fma_f32 v100, v90, v146, v100
	v_fma_f32 v101, v91, v147, v101
	v_cvt_pk_f16_f32 v90, v94, v95
	v_lshlrev_b64 v[94:95], 11, v[98:99]
	v_cvt_pk_f16_f32 v93, v92, v93
	v_cvt_pk_f16_f32 v91, v96, v97
	v_cvt_pk_f16_f32 v92, v100, v101
	v_lshl_add_u64 v[94:95], v[178:179], 0, v[94:95]
	global_store_dwordx4 v[94:95], v[90:93], off
	v_cvt_f32_f16_sdwa v95, v130 dst_sel:DWORD dst_unused:UNUSED_PAD src0_sel:WORD_1
	v_cvt_f32_f16_e32 v94, v130
	v_cvt_f32_f16_sdwa v93, v132 dst_sel:DWORD dst_unused:UNUSED_PAD src0_sel:WORD_1
	v_cvt_f32_f16_sdwa v97, v133 dst_sel:DWORD dst_unused:UNUSED_PAD src0_sel:WORD_1
	v_cvt_f32_f16_sdwa v101, v131 dst_sel:DWORD dst_unused:UNUSED_PAD src0_sel:WORD_1
	v_cvt_f32_f16_e32 v100, v131
	v_cvt_f32_f16_e32 v96, v133
	v_cvt_f32_f16_e32 v92, v132
	v_add_u32_e32 v90, 0x90, v80
	v_fma_f32 v76, v76, v150, v94
	v_fma_f32 v77, v77, v151, v95
	v_ashrrev_i32_e32 v91, 31, v90
	v_fma_f32 v78, v78, v152, v100
	v_fma_f32 v79, v79, v153, v101
	v_fma_f32 v74, v74, v148, v96
	v_fma_f32 v75, v75, v149, v97
	v_fma_f32 v92, v72, v146, v92
	v_fma_f32 v93, v73, v147, v93
	v_cvt_pk_f16_f32 v72, v76, v77
	v_lshlrev_b64 v[76:77], 11, v[90:91]
	v_cvt_pk_f16_f32 v75, v74, v75
	v_cvt_pk_f16_f32 v73, v78, v79
	v_cvt_pk_f16_f32 v74, v92, v93
	v_lshl_add_u64 v[76:77], v[178:179], 0, v[76:77]
	global_store_dwordx4 v[76:77], v[72:75], off
	v_cvt_f32_f16_sdwa v77, v126 dst_sel:DWORD dst_unused:UNUSED_PAD src0_sel:WORD_1
	v_cvt_f32_f16_e32 v76, v126
	v_cvt_f32_f16_sdwa v75, v128 dst_sel:DWORD dst_unused:UNUSED_PAD src0_sel:WORD_1
	v_cvt_f32_f16_sdwa v79, v129 dst_sel:DWORD dst_unused:UNUSED_PAD src0_sel:WORD_1
	v_cvt_f32_f16_sdwa v91, v127 dst_sel:DWORD dst_unused:UNUSED_PAD src0_sel:WORD_1
	v_cvt_f32_f16_e32 v90, v127
	v_cvt_f32_f16_e32 v78, v129
	v_cvt_f32_f16_e32 v74, v128
	v_add_u32_e32 v72, 0xa0, v80
	v_fma_f32 v60, v60, v150, v76
	v_fma_f32 v61, v61, v151, v77
	v_ashrrev_i32_e32 v73, 31, v72
	v_fma_f32 v62, v62, v152, v90
	v_fma_f32 v63, v63, v153, v91
	v_fma_f32 v58, v58, v148, v78
	v_fma_f32 v59, v59, v149, v79
	v_fma_f32 v74, v56, v146, v74
	v_fma_f32 v75, v57, v147, v75
	v_cvt_pk_f16_f32 v56, v60, v61
	v_lshlrev_b64 v[60:61], 11, v[72:73]
	v_cvt_pk_f16_f32 v59, v58, v59
	v_cvt_pk_f16_f32 v57, v62, v63
	v_cvt_pk_f16_f32 v58, v74, v75
	v_lshl_add_u64 v[60:61], v[178:179], 0, v[60:61]
	global_store_dwordx4 v[60:61], v[56:59], off
	v_cvt_f32_f16_sdwa v61, v114 dst_sel:DWORD dst_unused:UNUSED_PAD src0_sel:WORD_1
	v_cvt_f32_f16_e32 v60, v114
	v_cvt_f32_f16_sdwa v59, v116 dst_sel:DWORD dst_unused:UNUSED_PAD src0_sel:WORD_1
	v_cvt_f32_f16_sdwa v63, v117 dst_sel:DWORD dst_unused:UNUSED_PAD src0_sel:WORD_1
	v_cvt_f32_f16_sdwa v73, v115 dst_sel:DWORD dst_unused:UNUSED_PAD src0_sel:WORD_1
	v_cvt_f32_f16_e32 v72, v115
	v_cvt_f32_f16_e32 v62, v117
	v_cvt_f32_f16_e32 v58, v116
	v_add_u32_e32 v56, 0xb0, v80
	v_fma_f32 v44, v44, v150, v60
	v_fma_f32 v45, v45, v151, v61
	v_ashrrev_i32_e32 v57, 31, v56
	v_fma_f32 v46, v46, v152, v72
	v_fma_f32 v47, v47, v153, v73
	v_fma_f32 v42, v42, v148, v62
	v_fma_f32 v43, v43, v149, v63
	v_fma_f32 v58, v40, v146, v58
	v_fma_f32 v59, v41, v147, v59
	v_cvt_pk_f16_f32 v40, v44, v45
	v_lshlrev_b64 v[44:45], 11, v[56:57]
	v_cvt_pk_f16_f32 v43, v42, v43
	v_cvt_pk_f16_f32 v41, v46, v47
	v_cvt_pk_f16_f32 v42, v58, v59
	v_lshl_add_u64 v[44:45], v[178:179], 0, v[44:45]
	global_store_dwordx4 v[44:45], v[40:43], off

.LBB0_84:
	s_waitcnt vmcnt(3)
	v_cvt_f32_f16_sdwa v103, v76 dst_sel:DWORD dst_unused:UNUSED_PAD src0_sel:WORD_1
	v_cvt_f32_f16_sdwa v105, v78 dst_sel:DWORD dst_unused:UNUSED_PAD src0_sel:WORD_1
	v_cvt_f32_f16_sdwa v107, v79 dst_sel:DWORD dst_unused:UNUSED_PAD src0_sel:WORD_1
	v_cvt_f32_f16_sdwa v109, v77 dst_sel:DWORD dst_unused:UNUSED_PAD src0_sel:WORD_1
	v_cvt_f32_f16_e32 v108, v77
	v_cvt_f32_f16_e32 v106, v79
	v_cvt_f32_f16_e32 v104, v78
	v_cvt_f32_f16_e32 v102, v76
	v_fma_f32 v76, v88, v46, v108
	v_fma_f32 v77, v89, v47, v109
	v_fma_f32 v78, v84, v42, v106
	v_fma_f32 v79, v85, v43, v107
	v_fma_f32 v82, v82, v40, v104
	v_fma_f32 v83, v83, v41, v105
	v_fma_f32 v84, v86, v44, v102
	v_fma_f32 v85, v87, v45, v103
	v_cvt_pk_f16_f32 v79, v78, v79
	v_cvt_pk_f16_f32 v77, v76, v77
	v_cvt_pk_f16_f32 v78, v82, v83
	v_cvt_pk_f16_f32 v76, v84, v85
	global_store_dwordx4 v[100:101], v[76:79], off
	s_waitcnt vmcnt(3)
	v_cvt_f32_f16_sdwa v83, v75 dst_sel:DWORD dst_unused:UNUSED_PAD src0_sel:WORD_1
	v_cvt_f32_f16_sdwa v85, v73 dst_sel:DWORD dst_unused:UNUSED_PAD src0_sel:WORD_1
	v_cvt_f32_f16_sdwa v77, v72 dst_sel:DWORD dst_unused:UNUSED_PAD src0_sel:WORD_1
	v_cvt_f32_f16_sdwa v79, v74 dst_sel:DWORD dst_unused:UNUSED_PAD src0_sel:WORD_1
	v_cvt_f32_f16_e32 v84, v73
	v_cvt_f32_f16_e32 v82, v75
	v_cvt_f32_f16_e32 v78, v74
	v_cvt_f32_f16_e32 v76, v72
	v_fma_f32 v70, v70, v46, v84
	v_fma_f32 v71, v71, v47, v85
	v_fma_f32 v66, v66, v42, v82
	v_fma_f32 v67, v67, v43, v83
	v_fma_f32 v72, v64, v40, v78
	v_fma_f32 v73, v65, v41, v79
	v_fma_f32 v68, v68, v44, v76
	v_fma_f32 v69, v69, v45, v77
	v_cvt_pk_f16_f32 v67, v66, v67
	v_cvt_pk_f16_f32 v65, v70, v71
	v_cvt_pk_f16_f32 v66, v72, v73
	v_cvt_pk_f16_f32 v64, v68, v69
	global_store_dwordx4 v[96:97], v[64:67], off
	s_waitcnt vmcnt(3)
	v_cvt_f32_f16_sdwa v69, v63 dst_sel:DWORD dst_unused:UNUSED_PAD src0_sel:WORD_1
	v_cvt_f32_f16_sdwa v71, v61 dst_sel:DWORD dst_unused:UNUSED_PAD src0_sel:WORD_1
	v_cvt_f32_f16_sdwa v65, v60 dst_sel:DWORD dst_unused:UNUSED_PAD src0_sel:WORD_1
	v_cvt_f32_f16_sdwa v67, v62 dst_sel:DWORD dst_unused:UNUSED_PAD src0_sel:WORD_1
	v_cvt_f32_f16_e32 v70, v61
	v_cvt_f32_f16_e32 v68, v63
	v_cvt_f32_f16_e32 v66, v62
	v_cvt_f32_f16_e32 v64, v60
	v_fma_f32 v54, v54, v46, v70
	v_fma_f32 v55, v55, v47, v71
	v_fma_f32 v50, v50, v42, v68
	v_fma_f32 v51, v51, v43, v69
	v_fma_f32 v60, v48, v40, v66
	v_fma_f32 v61, v49, v41, v67
	v_fma_f32 v52, v52, v44, v64
	v_fma_f32 v53, v53, v45, v65
	v_cvt_pk_f16_f32 v51, v50, v51
	v_cvt_pk_f16_f32 v49, v54, v55
	v_cvt_pk_f16_f32 v50, v60, v61
	v_cvt_pk_f16_f32 v48, v52, v53
	global_store_dwordx4 v[94:95], v[48:51], off
	s_waitcnt vmcnt(3)
	v_cvt_f32_f16_sdwa v53, v59 dst_sel:DWORD dst_unused:UNUSED_PAD src0_sel:WORD_1
	v_cvt_f32_f16_sdwa v55, v57 dst_sel:DWORD dst_unused:UNUSED_PAD src0_sel:WORD_1
	v_cvt_f32_f16_sdwa v49, v56 dst_sel:DWORD dst_unused:UNUSED_PAD src0_sel:WORD_1
	v_cvt_f32_f16_sdwa v51, v58 dst_sel:DWORD dst_unused:UNUSED_PAD src0_sel:WORD_1
	v_cvt_f32_f16_e32 v54, v57
	v_cvt_f32_f16_e32 v52, v59
	v_cvt_f32_f16_e32 v50, v58
	v_cvt_f32_f16_e32 v48, v56
	v_fma_f32 v38, v38, v46, v54
	v_fma_f32 v39, v39, v47, v55
	v_fma_f32 v34, v34, v42, v52
	v_fma_f32 v35, v35, v43, v53
	v_fma_f32 v50, v32, v40, v50
	v_fma_f32 v51, v33, v41, v51
	v_fma_f32 v36, v36, v44, v48
	v_fma_f32 v37, v37, v45, v49
	v_cvt_pk_f16_f32 v35, v34, v35
	v_cvt_pk_f16_f32 v33, v38, v39
	v_cvt_pk_f16_f32 v34, v50, v51
	v_cvt_pk_f16_f32 v32, v36, v37
	s_and_b64 vcc, exec, s[36:37]
	global_store_dwordx4 v[92:93], v[32:35], off
	s_cbranch_vccnz .LBB0_86
	s_nop 0
	v_cvt_f32_f16_sdwa v35, v142 dst_sel:DWORD dst_unused:UNUSED_PAD src0_sel:WORD_1
	v_cvt_f32_f16_e32 v34, v142
	v_cvt_f32_f16_sdwa v33, v144 dst_sel:DWORD dst_unused:UNUSED_PAD src0_sel:WORD_1
	v_cvt_f32_f16_e32 v32, v144
	v_cvt_f32_f16_sdwa v37, v145 dst_sel:DWORD dst_unused:UNUSED_PAD src0_sel:WORD_1
	v_cvt_f32_f16_sdwa v39, v143 dst_sel:DWORD dst_unused:UNUSED_PAD src0_sel:WORD_1
	v_cvt_f32_f16_e32 v38, v143
	v_cvt_f32_f16_e32 v36, v145
	v_fma_f32 v28, v28, v44, v34
	v_fma_f32 v29, v29, v45, v35
	v_ashrrev_i32_e32 v99, 31, v98
	v_fma_f32 v32, v24, v40, v32
	v_fma_f32 v33, v25, v41, v33
	v_cvt_pk_f16_f32 v24, v28, v29
	v_lshlrev_b64 v[28:29], 11, v[98:99]
	v_fma_f32 v30, v30, v46, v38
	v_fma_f32 v31, v31, v47, v39
	v_fma_f32 v26, v26, v42, v36
	v_fma_f32 v27, v27, v43, v37
	v_lshl_add_u64 v[28:29], s[8:9], 0, v[28:29]
	v_cvt_pk_f16_f32 v27, v26, v27
	v_cvt_pk_f16_f32 v25, v30, v31
	v_cvt_pk_f16_f32 v26, v32, v33
	v_lshl_add_u64 v[28:29], v[28:29], 0, v[90:91]
	global_store_dwordx4 v[28:29], v[24:27], off
	v_cvt_f32_f16_sdwa v29, v130 dst_sel:DWORD dst_unused:UNUSED_PAD src0_sel:WORD_1
	v_cvt_f32_f16_e32 v28, v130
	v_cvt_f32_f16_sdwa v27, v132 dst_sel:DWORD dst_unused:UNUSED_PAD src0_sel:WORD_1
	v_cvt_f32_f16_e32 v26, v132
	v_cvt_f32_f16_sdwa v31, v133 dst_sel:DWORD dst_unused:UNUSED_PAD src0_sel:WORD_1
	v_cvt_f32_f16_sdwa v33, v131 dst_sel:DWORD dst_unused:UNUSED_PAD src0_sel:WORD_1
	v_cvt_f32_f16_e32 v32, v131
	v_cvt_f32_f16_e32 v30, v133
	v_add_u32_e32 v24, 0x90, v80
	v_fma_f32 v20, v20, v44, v28
	v_fma_f32 v21, v21, v45, v29
	v_ashrrev_i32_e32 v25, 31, v24
	v_fma_f32 v26, v16, v40, v26
	v_fma_f32 v27, v17, v41, v27
	v_cvt_pk_f16_f32 v16, v20, v21
	v_lshlrev_b64 v[20:21], 11, v[24:25]
	v_fma_f32 v22, v22, v46, v32
	v_fma_f32 v23, v23, v47, v33
	v_fma_f32 v18, v18, v42, v30
	v_fma_f32 v19, v19, v43, v31
	v_lshl_add_u64 v[20:21], s[8:9], 0, v[20:21]
	v_cvt_pk_f16_f32 v19, v18, v19
	v_cvt_pk_f16_f32 v17, v22, v23
	v_cvt_pk_f16_f32 v18, v26, v27
	v_lshl_add_u64 v[20:21], v[20:21], 0, v[90:91]
	global_store_dwordx4 v[20:21], v[16:19], off
	v_cvt_f32_f16_sdwa v21, v126 dst_sel:DWORD dst_unused:UNUSED_PAD src0_sel:WORD_1
	v_cvt_f32_f16_e32 v20, v126
	v_cvt_f32_f16_sdwa v19, v128 dst_sel:DWORD dst_unused:UNUSED_PAD src0_sel:WORD_1
	v_cvt_f32_f16_e32 v18, v128
	v_cvt_f32_f16_sdwa v23, v129 dst_sel:DWORD dst_unused:UNUSED_PAD src0_sel:WORD_1
	v_cvt_f32_f16_sdwa v25, v127 dst_sel:DWORD dst_unused:UNUSED_PAD src0_sel:WORD_1
	v_cvt_f32_f16_e32 v24, v127
	v_cvt_f32_f16_e32 v22, v129
	v_add_u32_e32 v16, 0xa0, v80
	v_fma_f32 v12, v12, v44, v20
	v_fma_f32 v13, v13, v45, v21
	v_ashrrev_i32_e32 v17, 31, v16
	v_fma_f32 v18, v8, v40, v18
	v_fma_f32 v19, v9, v41, v19
	v_cvt_pk_f16_f32 v8, v12, v13
	v_lshlrev_b64 v[12:13], 11, v[16:17]
	v_fma_f32 v14, v14, v46, v24
	v_fma_f32 v15, v15, v47, v25
	v_fma_f32 v10, v10, v42, v22
	v_fma_f32 v11, v11, v43, v23
	v_lshl_add_u64 v[12:13], s[8:9], 0, v[12:13]
	v_cvt_pk_f16_f32 v11, v10, v11
	v_cvt_pk_f16_f32 v9, v14, v15
	v_cvt_pk_f16_f32 v10, v18, v19
	v_lshl_add_u64 v[12:13], v[12:13], 0, v[90:91]
	global_store_dwordx4 v[12:13], v[8:11], off
	v_cvt_f32_f16_sdwa v13, v114 dst_sel:DWORD dst_unused:UNUSED_PAD src0_sel:WORD_1
	v_cvt_f32_f16_e32 v12, v114
	v_cvt_f32_f16_sdwa v11, v116 dst_sel:DWORD dst_unused:UNUSED_PAD src0_sel:WORD_1
	v_cvt_f32_f16_e32 v10, v116
	v_cvt_f32_f16_sdwa v15, v117 dst_sel:DWORD dst_unused:UNUSED_PAD src0_sel:WORD_1
	v_cvt_f32_f16_sdwa v17, v115 dst_sel:DWORD dst_unused:UNUSED_PAD src0_sel:WORD_1
	v_cvt_f32_f16_e32 v16, v115
	v_cvt_f32_f16_e32 v14, v117
	v_add_u32_e32 v8, 0xb0, v80
	v_fma_f32 v4, v4, v44, v12
	v_fma_f32 v5, v5, v45, v13
	v_ashrrev_i32_e32 v9, 31, v8
	v_fma_f32 v10, v0, v40, v10
	v_fma_f32 v11, v1, v41, v11
	v_cvt_pk_f16_f32 v0, v4, v5
	v_lshlrev_b64 v[4:5], 11, v[8:9]
	v_fma_f32 v6, v6, v46, v16
	v_fma_f32 v7, v7, v47, v17
	v_fma_f32 v2, v2, v42, v14
	v_fma_f32 v3, v3, v43, v15
	v_lshl_add_u64 v[4:5], s[8:9], 0, v[4:5]
	v_cvt_pk_f16_f32 v3, v2, v3
	v_cvt_pk_f16_f32 v1, v6, v7
	v_cvt_pk_f16_f32 v2, v10, v11
	v_lshl_add_u64 v[4:5], v[4:5], 0, v[90:91]
	global_store_dwordx4 v[4:5], v[0:3], off

.LBB0_423:
	s_waitcnt vmcnt(0)
	v_cvt_f32_f16_sdwa v191, v170 dst_sel:DWORD dst_unused:UNUSED_PAD src0_sel:WORD_1
	v_cvt_f32_f16_sdwa v193, v168 dst_sel:DWORD dst_unused:UNUSED_PAD src0_sel:WORD_1
	v_cvt_f32_f16_sdwa v195, v171 dst_sel:DWORD dst_unused:UNUSED_PAD src0_sel:WORD_1
	v_cvt_f32_f16_sdwa v199, v169 dst_sel:DWORD dst_unused:UNUSED_PAD src0_sel:WORD_1
	v_cvt_f32_f16_e32 v198, v169
	v_cvt_f32_f16_e32 v194, v171
	v_cvt_f32_f16_e32 v192, v168
	v_cvt_f32_f16_e32 v190, v170
	v_fma_f32 v138, v138, v154, v198
	v_fma_f32 v139, v139, v155, v199
	v_fma_f32 v134, v134, v150, v194
	v_fma_f32 v135, v135, v151, v195
	v_fma_f32 v136, v136, v152, v192
	v_fma_f32 v137, v137, v153, v193
	v_fma_f32 v168, v132, v148, v190
	v_fma_f32 v169, v133, v149, v191
	v_cvt_pk_f16_f32 v135, v134, v135
	v_cvt_pk_f16_f32 v133, v138, v139
	v_cvt_pk_f16_f32 v134, v168, v169
	v_cvt_pk_f16_f32 v132, v136, v137
	v_cvt_f32_f16_sdwa v137, v164 dst_sel:DWORD dst_unused:UNUSED_PAD src0_sel:WORD_1
	v_cvt_f32_f16_e32 v136, v164
	global_store_dwordx4 v[188:189], v[132:135], off
	v_cvt_f32_f16_sdwa v139, v167 dst_sel:DWORD dst_unused:UNUSED_PAD src0_sel:WORD_1
	v_cvt_f32_f16_sdwa v169, v165 dst_sel:DWORD dst_unused:UNUSED_PAD src0_sel:WORD_1
	v_cvt_f32_f16_sdwa v135, v166 dst_sel:DWORD dst_unused:UNUSED_PAD src0_sel:WORD_1
	v_cvt_f32_f16_e32 v168, v165
	v_cvt_f32_f16_e32 v138, v167
	v_cvt_f32_f16_e32 v134, v166
	v_add_u32_e32 v132, 16, v172
	v_fma_f32 v120, v120, v152, v136
	v_fma_f32 v121, v121, v153, v137
	v_ashrrev_i32_e32 v133, 31, v132
	v_fma_f32 v122, v122, v154, v168
	v_fma_f32 v123, v123, v155, v169
	v_fma_f32 v118, v118, v150, v138
	v_fma_f32 v119, v119, v151, v139
	v_fma_f32 v134, v116, v148, v134
	v_fma_f32 v135, v117, v149, v135
	v_cvt_pk_f16_f32 v116, v120, v121
	v_lshlrev_b64 v[120:121], 11, v[132:133]
	v_cvt_pk_f16_f32 v119, v118, v119
	v_cvt_pk_f16_f32 v117, v122, v123
	v_cvt_pk_f16_f32 v118, v134, v135
	v_lshl_add_u64 v[120:121], v[186:187], 0, v[120:121]
	global_store_dwordx4 v[120:121], v[116:119], off
	v_cvt_f32_f16_sdwa v121, v160 dst_sel:DWORD dst_unused:UNUSED_PAD src0_sel:WORD_1
	v_cvt_f32_f16_e32 v120, v160
	v_cvt_f32_f16_sdwa v119, v162 dst_sel:DWORD dst_unused:UNUSED_PAD src0_sel:WORD_1
	v_cvt_f32_f16_sdwa v123, v163 dst_sel:DWORD dst_unused:UNUSED_PAD src0_sel:WORD_1
	v_cvt_f32_f16_sdwa v133, v161 dst_sel:DWORD dst_unused:UNUSED_PAD src0_sel:WORD_1
	v_cvt_f32_f16_e32 v132, v161
	v_cvt_f32_f16_e32 v122, v163
	v_cvt_f32_f16_e32 v118, v162
	v_add_u32_e32 v116, 32, v172
	v_fma_f32 v112, v112, v152, v120
	v_fma_f32 v113, v113, v153, v121
	v_ashrrev_i32_e32 v117, 31, v116
	v_fma_f32 v114, v114, v154, v132
	v_fma_f32 v115, v115, v155, v133
	v_fma_f32 v110, v110, v150, v122
	v_fma_f32 v111, v111, v151, v123
	v_fma_f32 v118, v108, v148, v118
	v_fma_f32 v119, v109, v149, v119
	v_cvt_pk_f16_f32 v108, v112, v113
	v_lshlrev_b64 v[112:113], 11, v[116:117]
	v_cvt_pk_f16_f32 v111, v110, v111
	v_cvt_pk_f16_f32 v109, v114, v115
	v_cvt_pk_f16_f32 v110, v118, v119
	v_lshl_add_u64 v[112:113], v[186:187], 0, v[112:113]
	global_store_dwordx4 v[112:113], v[108:111], off
	v_cvt_f32_f16_sdwa v113, v156 dst_sel:DWORD dst_unused:UNUSED_PAD src0_sel:WORD_1
	v_cvt_f32_f16_e32 v112, v156
	v_cvt_f32_f16_sdwa v111, v158 dst_sel:DWORD dst_unused:UNUSED_PAD src0_sel:WORD_1
	v_cvt_f32_f16_sdwa v115, v159 dst_sel:DWORD dst_unused:UNUSED_PAD src0_sel:WORD_1
	v_cvt_f32_f16_sdwa v117, v157 dst_sel:DWORD dst_unused:UNUSED_PAD src0_sel:WORD_1
	v_cvt_f32_f16_e32 v116, v157
	v_cvt_f32_f16_e32 v114, v159
	v_cvt_f32_f16_e32 v110, v158
	v_add_u32_e32 v108, 48, v172
	v_fma_f32 v104, v104, v152, v112
	v_fma_f32 v105, v105, v153, v113
	v_ashrrev_i32_e32 v109, 31, v108
	v_fma_f32 v106, v106, v154, v116
	v_fma_f32 v107, v107, v155, v117
	v_fma_f32 v102, v102, v150, v114
	v_fma_f32 v103, v103, v151, v115
	v_fma_f32 v110, v100, v148, v110
	v_fma_f32 v111, v101, v149, v111
	v_cvt_pk_f16_f32 v100, v104, v105
	v_lshlrev_b64 v[104:105], 11, v[108:109]
	v_cvt_pk_f16_f32 v103, v102, v103
	v_cvt_pk_f16_f32 v101, v106, v107
	v_cvt_pk_f16_f32 v102, v110, v111
	v_lshl_add_u64 v[104:105], v[186:187], 0, v[104:105]
	global_store_dwordx4 v[104:105], v[100:103], off
	s_and_b64 vcc, exec, s[36:37]
	s_nop 0
	v_add_u32_e32 v100, 0x80, v80
	s_cbranch_vccnz .LBB0_425
	v_cvt_f32_f16_sdwa v105, v144 dst_sel:DWORD dst_unused:UNUSED_PAD src0_sel:WORD_1
	v_cvt_f32_f16_e32 v104, v144
	v_cvt_f32_f16_sdwa v103, v146 dst_sel:DWORD dst_unused:UNUSED_PAD src0_sel:WORD_1
	v_cvt_f32_f16_sdwa v107, v147 dst_sel:DWORD dst_unused:UNUSED_PAD src0_sel:WORD_1
	v_cvt_f32_f16_sdwa v109, v145 dst_sel:DWORD dst_unused:UNUSED_PAD src0_sel:WORD_1
	v_cvt_f32_f16_e32 v108, v145
	v_cvt_f32_f16_e32 v106, v147
	v_cvt_f32_f16_e32 v102, v146
	v_fma_f32 v96, v96, v152, v104
	v_fma_f32 v97, v97, v153, v105
	v_ashrrev_i32_e32 v101, 31, v100
	v_fma_f32 v98, v98, v154, v108
	v_fma_f32 v99, v99, v155, v109
	v_fma_f32 v94, v94, v150, v106
	v_fma_f32 v95, v95, v151, v107
	v_fma_f32 v102, v92, v148, v102
	v_fma_f32 v103, v93, v149, v103
	v_cvt_pk_f16_f32 v92, v96, v97
	v_lshlrev_b64 v[96:97], 11, v[100:101]
	v_cvt_pk_f16_f32 v95, v94, v95
	v_cvt_pk_f16_f32 v93, v98, v99
	v_cvt_pk_f16_f32 v94, v102, v103
	v_lshl_add_u64 v[96:97], v[186:187], 0, v[96:97]
	global_store_dwordx4 v[96:97], v[92:95], off
	v_cvt_f32_f16_sdwa v97, v140 dst_sel:DWORD dst_unused:UNUSED_PAD src0_sel:WORD_1
	v_cvt_f32_f16_e32 v96, v140
	v_cvt_f32_f16_sdwa v95, v142 dst_sel:DWORD dst_unused:UNUSED_PAD src0_sel:WORD_1
	v_cvt_f32_f16_sdwa v99, v143 dst_sel:DWORD dst_unused:UNUSED_PAD src0_sel:WORD_1
	v_cvt_f32_f16_sdwa v103, v141 dst_sel:DWORD dst_unused:UNUSED_PAD src0_sel:WORD_1
	v_cvt_f32_f16_e32 v102, v141
	v_cvt_f32_f16_e32 v98, v143
	v_cvt_f32_f16_e32 v94, v142
	v_add_u32_e32 v92, 0x90, v80
	v_fma_f32 v88, v88, v152, v96
	v_fma_f32 v89, v89, v153, v97
	v_ashrrev_i32_e32 v93, 31, v92
	v_fma_f32 v90, v90, v154, v102
	v_fma_f32 v91, v91, v155, v103
	v_fma_f32 v86, v86, v150, v98
	v_fma_f32 v87, v87, v151, v99
	v_fma_f32 v94, v84, v148, v94
	v_fma_f32 v95, v85, v149, v95
	v_cvt_pk_f16_f32 v84, v88, v89
	v_lshlrev_b64 v[88:89], 11, v[92:93]
	v_cvt_pk_f16_f32 v87, v86, v87
	v_cvt_pk_f16_f32 v85, v90, v91
	v_cvt_pk_f16_f32 v86, v94, v95
	v_lshl_add_u64 v[88:89], v[186:187], 0, v[88:89]
	global_store_dwordx4 v[88:89], v[84:87], off
	v_cvt_f32_f16_sdwa v89, v128 dst_sel:DWORD dst_unused:UNUSED_PAD src0_sel:WORD_1
	v_cvt_f32_f16_e32 v88, v128
	v_cvt_f32_f16_sdwa v87, v130 dst_sel:DWORD dst_unused:UNUSED_PAD src0_sel:WORD_1
	v_cvt_f32_f16_sdwa v91, v131 dst_sel:DWORD dst_unused:UNUSED_PAD src0_sel:WORD_1
	v_cvt_f32_f16_sdwa v93, v129 dst_sel:DWORD dst_unused:UNUSED_PAD src0_sel:WORD_1
	v_cvt_f32_f16_e32 v92, v129
	v_cvt_f32_f16_e32 v90, v131
	v_cvt_f32_f16_e32 v86, v130
	v_add_u32_e32 v84, 0xa0, v80
	v_fma_f32 v68, v68, v152, v88
	v_fma_f32 v69, v69, v153, v89
	v_ashrrev_i32_e32 v85, 31, v84
	v_fma_f32 v70, v70, v154, v92
	v_fma_f32 v71, v71, v155, v93
	v_fma_f32 v66, v66, v150, v90
	v_fma_f32 v67, v67, v151, v91
	v_fma_f32 v86, v64, v148, v86
	v_fma_f32 v87, v65, v149, v87
	v_cvt_pk_f16_f32 v64, v68, v69
	v_lshlrev_b64 v[68:69], 11, v[84:85]
	v_cvt_pk_f16_f32 v67, v66, v67
	v_cvt_pk_f16_f32 v65, v70, v71
	v_cvt_pk_f16_f32 v66, v86, v87
	v_lshl_add_u64 v[68:69], v[186:187], 0, v[68:69]
	global_store_dwordx4 v[68:69], v[64:67], off
	v_cvt_f32_f16_sdwa v69, v124 dst_sel:DWORD dst_unused:UNUSED_PAD src0_sel:WORD_1
	v_cvt_f32_f16_e32 v68, v124
	v_cvt_f32_f16_sdwa v67, v126 dst_sel:DWORD dst_unused:UNUSED_PAD src0_sel:WORD_1
	v_cvt_f32_f16_sdwa v71, v127 dst_sel:DWORD dst_unused:UNUSED_PAD src0_sel:WORD_1
	v_cvt_f32_f16_sdwa v85, v125 dst_sel:DWORD dst_unused:UNUSED_PAD src0_sel:WORD_1
	v_cvt_f32_f16_e32 v84, v125
	v_cvt_f32_f16_e32 v70, v127
	v_cvt_f32_f16_e32 v66, v126
	v_add_u32_e32 v64, 0xb0, v80
	v_fma_f32 v52, v52, v152, v68
	v_fma_f32 v53, v53, v153, v69
	v_ashrrev_i32_e32 v65, 31, v64
	v_fma_f32 v54, v54, v154, v84
	v_fma_f32 v55, v55, v155, v85
	v_fma_f32 v50, v50, v150, v70
	v_fma_f32 v51, v51, v151, v71
	v_fma_f32 v66, v48, v148, v66
	v_fma_f32 v67, v49, v149, v67
	v_cvt_pk_f16_f32 v48, v52, v53
	v_lshlrev_b64 v[52:53], 11, v[64:65]
	v_cvt_pk_f16_f32 v51, v50, v51
	v_cvt_pk_f16_f32 v49, v54, v55
	v_cvt_pk_f16_f32 v50, v66, v67
	v_lshl_add_u64 v[52:53], v[186:187], 0, v[52:53]
	global_store_dwordx4 v[52:53], v[48:51], off
.LBB0_425:
	global_load_dwordx4 v[48:51], v[174:175], off offset:528
	s_nop 0
	global_load_dwordx4 v[52:55], v[174:175], off offset:512
	s_and_b64 vcc, exec, s[38:39]
	s_cbranch_vccnz .LBB0_427
	global_load_dwordx4 v[64:67], v[176:177], off offset:512
	global_load_dwordx4 v[68:71], v[176:177], off offset:528
	s_waitcnt vmcnt(1)
	v_mul_f32_e32 v54, v54, v66
	v_mul_f32_e32 v55, v55, v67
	v_mul_f32_e32 v52, v52, v64
	v_mul_f32_e32 v53, v53, v65
	s_waitcnt vmcnt(0)
	v_mul_f32_e32 v50, v50, v70
	v_mul_f32_e32 v51, v51, v71
	v_mul_f32_e32 v48, v48, v68
	v_mul_f32_e32 v49, v49, v69

.LBB0_431:
	s_waitcnt vmcnt(3)
	v_cvt_f32_f16_sdwa v103, v88 dst_sel:DWORD dst_unused:UNUSED_PAD src0_sel:WORD_1
	v_cvt_f32_f16_sdwa v105, v86 dst_sel:DWORD dst_unused:UNUSED_PAD src0_sel:WORD_1
	v_cvt_f32_f16_sdwa v107, v89 dst_sel:DWORD dst_unused:UNUSED_PAD src0_sel:WORD_1
	v_cvt_f32_f16_sdwa v109, v87 dst_sel:DWORD dst_unused:UNUSED_PAD src0_sel:WORD_1
	v_cvt_f32_f16_e32 v108, v87
	v_cvt_f32_f16_e32 v106, v89
	v_cvt_f32_f16_e32 v104, v86
	v_cvt_f32_f16_e32 v102, v88
	v_fma_f32 v78, v78, v54, v108
	v_fma_f32 v79, v79, v55, v109
	v_fma_f32 v74, v74, v50, v106
	v_fma_f32 v75, v75, v51, v107
	v_fma_f32 v76, v76, v52, v104
	v_fma_f32 v77, v77, v53, v105
	v_fma_f32 v86, v72, v48, v102
	v_fma_f32 v87, v73, v49, v103
	v_cvt_pk_f16_f32 v75, v74, v75
	v_cvt_pk_f16_f32 v73, v78, v79
	v_cvt_pk_f16_f32 v74, v86, v87
	v_cvt_pk_f16_f32 v72, v76, v77
	global_store_dwordx4 v[98:99], v[72:75], off
	s_waitcnt vmcnt(3)
	v_cvt_f32_f16_sdwa v77, v85 dst_sel:DWORD dst_unused:UNUSED_PAD src0_sel:WORD_1
	v_cvt_f32_f16_sdwa v79, v83 dst_sel:DWORD dst_unused:UNUSED_PAD src0_sel:WORD_1
	v_cvt_f32_f16_sdwa v73, v84 dst_sel:DWORD dst_unused:UNUSED_PAD src0_sel:WORD_1
	v_cvt_f32_f16_sdwa v75, v82 dst_sel:DWORD dst_unused:UNUSED_PAD src0_sel:WORD_1
	v_cvt_f32_f16_e32 v78, v83
	v_cvt_f32_f16_e32 v76, v85
	v_cvt_f32_f16_e32 v74, v82
	v_cvt_f32_f16_e32 v72, v84
	v_fma_f32 v62, v62, v54, v78
	v_fma_f32 v63, v63, v55, v79
	v_fma_f32 v58, v58, v50, v76
	v_fma_f32 v59, v59, v51, v77
	v_fma_f32 v60, v60, v52, v74
	v_fma_f32 v61, v61, v53, v75
	v_fma_f32 v72, v56, v48, v72
	v_fma_f32 v73, v57, v49, v73
	v_cvt_pk_f16_f32 v59, v58, v59
	v_cvt_pk_f16_f32 v57, v62, v63
	v_cvt_pk_f16_f32 v58, v72, v73
	v_cvt_pk_f16_f32 v56, v60, v61
	global_store_dwordx4 v[96:97], v[56:59], off
	s_waitcnt vmcnt(3)
	v_cvt_f32_f16_sdwa v61, v71 dst_sel:DWORD dst_unused:UNUSED_PAD src0_sel:WORD_1
	v_cvt_f32_f16_sdwa v63, v69 dst_sel:DWORD dst_unused:UNUSED_PAD src0_sel:WORD_1
	v_cvt_f32_f16_sdwa v57, v70 dst_sel:DWORD dst_unused:UNUSED_PAD src0_sel:WORD_1
	v_cvt_f32_f16_sdwa v59, v68 dst_sel:DWORD dst_unused:UNUSED_PAD src0_sel:WORD_1
	v_cvt_f32_f16_e32 v62, v69
	v_cvt_f32_f16_e32 v60, v71
	v_cvt_f32_f16_e32 v58, v68
	v_cvt_f32_f16_e32 v56, v70
	v_fma_f32 v46, v46, v54, v62
	v_fma_f32 v47, v47, v55, v63
	v_fma_f32 v42, v42, v50, v60
	v_fma_f32 v43, v43, v51, v61
	v_fma_f32 v44, v44, v52, v58
	v_fma_f32 v45, v45, v53, v59
	v_fma_f32 v56, v40, v48, v56
	v_fma_f32 v57, v41, v49, v57
	v_cvt_pk_f16_f32 v43, v42, v43
	v_cvt_pk_f16_f32 v41, v46, v47
	v_cvt_pk_f16_f32 v42, v56, v57
	v_cvt_pk_f16_f32 v40, v44, v45
	global_store_dwordx4 v[94:95], v[40:43], off
	s_waitcnt vmcnt(3)
	v_cvt_f32_f16_sdwa v45, v67 dst_sel:DWORD dst_unused:UNUSED_PAD src0_sel:WORD_1
	v_cvt_f32_f16_sdwa v47, v65 dst_sel:DWORD dst_unused:UNUSED_PAD src0_sel:WORD_1
	v_cvt_f32_f16_sdwa v41, v66 dst_sel:DWORD dst_unused:UNUSED_PAD src0_sel:WORD_1
	v_cvt_f32_f16_sdwa v43, v64 dst_sel:DWORD dst_unused:UNUSED_PAD src0_sel:WORD_1
	v_cvt_f32_f16_e32 v46, v65
	v_cvt_f32_f16_e32 v44, v67
	v_cvt_f32_f16_e32 v42, v64
	v_cvt_f32_f16_e32 v40, v66
	v_fma_f32 v38, v38, v54, v46
	v_fma_f32 v39, v39, v55, v47
	v_fma_f32 v34, v34, v50, v44
	v_fma_f32 v35, v35, v51, v45
	v_fma_f32 v36, v36, v52, v42
	v_fma_f32 v37, v37, v53, v43
	v_fma_f32 v40, v32, v48, v40
	v_fma_f32 v41, v33, v49, v41
	v_cvt_pk_f16_f32 v35, v34, v35
	v_cvt_pk_f16_f32 v33, v38, v39
	v_cvt_pk_f16_f32 v34, v40, v41
	v_cvt_pk_f16_f32 v32, v36, v37
	s_and_b64 vcc, exec, s[36:37]
	global_store_dwordx4 v[92:93], v[32:35], off
	s_cbranch_vccz .LBB0_443
	s_andn2_b64 vcc, exec, s[44:45]
	s_mov_b64 s[36:37], -1
	s_cbranch_vccnz .LBB0_396
	s_branch .LBB0_444

.LBB0_443:
	s_nop 0
	v_cvt_f32_f16_sdwa v35, v144 dst_sel:DWORD dst_unused:UNUSED_PAD src0_sel:WORD_1
	v_cvt_f32_f16_e32 v34, v144
	v_cvt_f32_f16_sdwa v33, v146 dst_sel:DWORD dst_unused:UNUSED_PAD src0_sel:WORD_1
	v_cvt_f32_f16_e32 v32, v146
	v_cvt_f32_f16_sdwa v37, v147 dst_sel:DWORD dst_unused:UNUSED_PAD src0_sel:WORD_1
	v_cvt_f32_f16_sdwa v39, v145 dst_sel:DWORD dst_unused:UNUSED_PAD src0_sel:WORD_1
	v_cvt_f32_f16_e32 v38, v145
	v_cvt_f32_f16_e32 v36, v147
	v_fma_f32 v28, v28, v52, v34
	v_fma_f32 v29, v29, v53, v35
	v_ashrrev_i32_e32 v101, 31, v100
	v_fma_f32 v32, v24, v48, v32
	v_fma_f32 v33, v25, v49, v33
	v_cvt_pk_f16_f32 v24, v28, v29
	v_lshlrev_b64 v[28:29], 11, v[100:101]
	v_fma_f32 v30, v30, v54, v38
	v_fma_f32 v31, v31, v55, v39
	v_fma_f32 v26, v26, v50, v36
	v_fma_f32 v27, v27, v51, v37
	v_lshl_add_u64 v[28:29], s[6:7], 0, v[28:29]
	v_cvt_pk_f16_f32 v27, v26, v27
	v_cvt_pk_f16_f32 v25, v30, v31
	v_cvt_pk_f16_f32 v26, v32, v33
	v_lshl_add_u64 v[28:29], v[28:29], 0, v[90:91]
	global_store_dwordx4 v[28:29], v[24:27], off
	v_cvt_f32_f16_sdwa v29, v140 dst_sel:DWORD dst_unused:UNUSED_PAD src0_sel:WORD_1
	v_cvt_f32_f16_e32 v28, v140
	v_cvt_f32_f16_sdwa v27, v142 dst_sel:DWORD dst_unused:UNUSED_PAD src0_sel:WORD_1
	v_cvt_f32_f16_e32 v26, v142
	v_cvt_f32_f16_sdwa v31, v143 dst_sel:DWORD dst_unused:UNUSED_PAD src0_sel:WORD_1
	v_cvt_f32_f16_sdwa v33, v141 dst_sel:DWORD dst_unused:UNUSED_PAD src0_sel:WORD_1
	v_cvt_f32_f16_e32 v32, v141
	v_cvt_f32_f16_e32 v30, v143
	v_add_u32_e32 v24, 0x90, v80
	v_fma_f32 v20, v20, v52, v28
	v_fma_f32 v21, v21, v53, v29
	v_ashrrev_i32_e32 v25, 31, v24
	v_fma_f32 v26, v16, v48, v26
	v_fma_f32 v27, v17, v49, v27
	v_cvt_pk_f16_f32 v16, v20, v21
	v_lshlrev_b64 v[20:21], 11, v[24:25]
	v_fma_f32 v22, v22, v54, v32
	v_fma_f32 v23, v23, v55, v33
	v_fma_f32 v18, v18, v50, v30
	v_fma_f32 v19, v19, v51, v31
	v_lshl_add_u64 v[20:21], s[6:7], 0, v[20:21]
	v_cvt_pk_f16_f32 v19, v18, v19
	v_cvt_pk_f16_f32 v17, v22, v23
	v_cvt_pk_f16_f32 v18, v26, v27
	v_lshl_add_u64 v[20:21], v[20:21], 0, v[90:91]
	global_store_dwordx4 v[20:21], v[16:19], off
	v_cvt_f32_f16_sdwa v21, v128 dst_sel:DWORD dst_unused:UNUSED_PAD src0_sel:WORD_1
	v_cvt_f32_f16_e32 v20, v128
	v_cvt_f32_f16_sdwa v19, v130 dst_sel:DWORD dst_unused:UNUSED_PAD src0_sel:WORD_1
	v_cvt_f32_f16_e32 v18, v130
	v_cvt_f32_f16_sdwa v23, v131 dst_sel:DWORD dst_unused:UNUSED_PAD src0_sel:WORD_1
	v_cvt_f32_f16_sdwa v25, v129 dst_sel:DWORD dst_unused:UNUSED_PAD src0_sel:WORD_1
	v_cvt_f32_f16_e32 v24, v129
	v_cvt_f32_f16_e32 v22, v131
	v_add_u32_e32 v16, 0xa0, v80
	v_fma_f32 v12, v12, v52, v20
	v_fma_f32 v13, v13, v53, v21
	v_ashrrev_i32_e32 v17, 31, v16
	v_fma_f32 v18, v8, v48, v18
	v_fma_f32 v19, v9, v49, v19
	v_cvt_pk_f16_f32 v8, v12, v13
	v_lshlrev_b64 v[12:13], 11, v[16:17]
	v_fma_f32 v14, v14, v54, v24
	v_fma_f32 v15, v15, v55, v25
	v_fma_f32 v10, v10, v50, v22
	v_fma_f32 v11, v11, v51, v23
	v_lshl_add_u64 v[12:13], s[6:7], 0, v[12:13]
	v_cvt_pk_f16_f32 v11, v10, v11
	v_cvt_pk_f16_f32 v9, v14, v15
	v_cvt_pk_f16_f32 v10, v18, v19
	v_lshl_add_u64 v[12:13], v[12:13], 0, v[90:91]
	global_store_dwordx4 v[12:13], v[8:11], off
	v_cvt_f32_f16_sdwa v13, v124 dst_sel:DWORD dst_unused:UNUSED_PAD src0_sel:WORD_1
	v_cvt_f32_f16_e32 v12, v124
	v_cvt_f32_f16_sdwa v11, v126 dst_sel:DWORD dst_unused:UNUSED_PAD src0_sel:WORD_1
	v_cvt_f32_f16_e32 v10, v126
	v_cvt_f32_f16_sdwa v15, v127 dst_sel:DWORD dst_unused:UNUSED_PAD src0_sel:WORD_1
	v_cvt_f32_f16_sdwa v17, v125 dst_sel:DWORD dst_unused:UNUSED_PAD src0_sel:WORD_1
	v_cvt_f32_f16_e32 v16, v125
	v_cvt_f32_f16_e32 v14, v127
	v_add_u32_e32 v8, 0xb0, v80
	v_fma_f32 v4, v4, v52, v12
	v_fma_f32 v5, v5, v53, v13
	v_ashrrev_i32_e32 v9, 31, v8
	v_fma_f32 v10, v0, v48, v10
	v_fma_f32 v11, v1, v49, v11
	v_cvt_pk_f16_f32 v0, v4, v5
	v_lshlrev_b64 v[4:5], 11, v[8:9]
	v_fma_f32 v6, v6, v54, v16
	v_fma_f32 v7, v7, v55, v17
	v_fma_f32 v2, v2, v50, v14
	v_fma_f32 v3, v3, v51, v15
	v_lshl_add_u64 v[4:5], s[6:7], 0, v[4:5]
	v_cvt_pk_f16_f32 v3, v2, v3
	v_cvt_pk_f16_f32 v1, v6, v7
	v_cvt_pk_f16_f32 v2, v10, v11
	v_lshl_add_u64 v[4:5], v[4:5], 0, v[90:91]
	global_store_dwordx4 v[4:5], v[0:3], off
	s_andn2_b64 vcc, exec, s[44:45]
	s_mov_b64 s[36:37], -1
	s_cbranch_vccnz .LBB0_396

.LBB0_623:
	s_waitcnt vmcnt(3)
	v_cvt_f32_f16_sdwa v103, v76 dst_sel:DWORD dst_unused:UNUSED_PAD src0_sel:WORD_1
	v_cvt_f32_f16_sdwa v105, v78 dst_sel:DWORD dst_unused:UNUSED_PAD src0_sel:WORD_1
	v_cvt_f32_f16_sdwa v107, v79 dst_sel:DWORD dst_unused:UNUSED_PAD src0_sel:WORD_1
	v_cvt_f32_f16_sdwa v109, v77 dst_sel:DWORD dst_unused:UNUSED_PAD src0_sel:WORD_1
	v_cvt_f32_f16_e32 v108, v77
	v_cvt_f32_f16_e32 v106, v79
	v_cvt_f32_f16_e32 v104, v78
	v_cvt_f32_f16_e32 v102, v76
	v_fma_f32 v76, v88, v46, v108
	v_fma_f32 v77, v89, v47, v109
	v_fma_f32 v78, v84, v42, v106
	v_fma_f32 v79, v85, v43, v107
	v_fma_f32 v82, v82, v40, v104
	v_fma_f32 v83, v83, v41, v105
	v_fma_f32 v84, v86, v44, v102
	v_fma_f32 v85, v87, v45, v103
	v_cvt_pk_f16_f32 v79, v78, v79
	v_cvt_pk_f16_f32 v77, v76, v77
	v_cvt_pk_f16_f32 v78, v82, v83
	v_cvt_pk_f16_f32 v76, v84, v85
	global_store_dwordx4 v[100:101], v[76:79], off
	s_waitcnt vmcnt(3)
	v_cvt_f32_f16_sdwa v83, v75 dst_sel:DWORD dst_unused:UNUSED_PAD src0_sel:WORD_1
	v_cvt_f32_f16_sdwa v85, v73 dst_sel:DWORD dst_unused:UNUSED_PAD src0_sel:WORD_1
	v_cvt_f32_f16_sdwa v77, v72 dst_sel:DWORD dst_unused:UNUSED_PAD src0_sel:WORD_1
	v_cvt_f32_f16_sdwa v79, v74 dst_sel:DWORD dst_unused:UNUSED_PAD src0_sel:WORD_1
	v_cvt_f32_f16_e32 v84, v73
	v_cvt_f32_f16_e32 v82, v75
	v_cvt_f32_f16_e32 v78, v74
	v_cvt_f32_f16_e32 v76, v72
	v_fma_f32 v70, v70, v46, v84
	v_fma_f32 v71, v71, v47, v85
	v_fma_f32 v66, v66, v42, v82
	v_fma_f32 v67, v67, v43, v83
	v_fma_f32 v72, v64, v40, v78
	v_fma_f32 v73, v65, v41, v79
	v_fma_f32 v68, v68, v44, v76
	v_fma_f32 v69, v69, v45, v77
	v_cvt_pk_f16_f32 v67, v66, v67
	v_cvt_pk_f16_f32 v65, v70, v71
	v_cvt_pk_f16_f32 v66, v72, v73
	v_cvt_pk_f16_f32 v64, v68, v69
	global_store_dwordx4 v[96:97], v[64:67], off
	s_waitcnt vmcnt(3)
	v_cvt_f32_f16_sdwa v69, v63 dst_sel:DWORD dst_unused:UNUSED_PAD src0_sel:WORD_1
	v_cvt_f32_f16_sdwa v71, v61 dst_sel:DWORD dst_unused:UNUSED_PAD src0_sel:WORD_1
	v_cvt_f32_f16_sdwa v65, v60 dst_sel:DWORD dst_unused:UNUSED_PAD src0_sel:WORD_1
	v_cvt_f32_f16_sdwa v67, v62 dst_sel:DWORD dst_unused:UNUSED_PAD src0_sel:WORD_1
	v_cvt_f32_f16_e32 v70, v61
	v_cvt_f32_f16_e32 v68, v63
	v_cvt_f32_f16_e32 v66, v62
	v_cvt_f32_f16_e32 v64, v60
	v_fma_f32 v54, v54, v46, v70
	v_fma_f32 v55, v55, v47, v71
	v_fma_f32 v50, v50, v42, v68
	v_fma_f32 v51, v51, v43, v69
	v_fma_f32 v60, v48, v40, v66
	v_fma_f32 v61, v49, v41, v67
	v_fma_f32 v52, v52, v44, v64
	v_fma_f32 v53, v53, v45, v65
	v_cvt_pk_f16_f32 v51, v50, v51
	v_cvt_pk_f16_f32 v49, v54, v55
	v_cvt_pk_f16_f32 v50, v60, v61
	v_cvt_pk_f16_f32 v48, v52, v53
	global_store_dwordx4 v[94:95], v[48:51], off
	s_waitcnt vmcnt(3)
	v_cvt_f32_f16_sdwa v53, v59 dst_sel:DWORD dst_unused:UNUSED_PAD src0_sel:WORD_1
	v_cvt_f32_f16_sdwa v55, v57 dst_sel:DWORD dst_unused:UNUSED_PAD src0_sel:WORD_1
	v_cvt_f32_f16_sdwa v49, v56 dst_sel:DWORD dst_unused:UNUSED_PAD src0_sel:WORD_1
	v_cvt_f32_f16_sdwa v51, v58 dst_sel:DWORD dst_unused:UNUSED_PAD src0_sel:WORD_1
	v_cvt_f32_f16_e32 v54, v57
	v_cvt_f32_f16_e32 v52, v59
	v_cvt_f32_f16_e32 v50, v58
	v_cvt_f32_f16_e32 v48, v56
	v_fma_f32 v38, v38, v46, v54
	v_fma_f32 v39, v39, v47, v55
	v_fma_f32 v34, v34, v42, v52
	v_fma_f32 v35, v35, v43, v53
	v_fma_f32 v50, v32, v40, v50
	v_fma_f32 v51, v33, v41, v51
	v_fma_f32 v36, v36, v44, v48
	v_fma_f32 v37, v37, v45, v49
	v_cvt_pk_f16_f32 v35, v34, v35
	v_cvt_pk_f16_f32 v33, v38, v39
	v_cvt_pk_f16_f32 v34, v50, v51
	v_cvt_pk_f16_f32 v32, v36, v37
	s_and_b64 vcc, exec, s[36:37]
	global_store_dwordx4 v[92:93], v[32:35], off
	s_cbranch_vccz .LBB0_636
	s_andn2_b64 vcc, exec, s[42:43]
	s_mov_b64 s[36:37], -1
	s_cbranch_vccnz .LBB0_597
	s_branch .LBB0_637

.LBB0_636:
	s_nop 0
	v_cvt_f32_f16_sdwa v35, v142 dst_sel:DWORD dst_unused:UNUSED_PAD src0_sel:WORD_1
	v_cvt_f32_f16_e32 v34, v142
	v_cvt_f32_f16_sdwa v33, v144 dst_sel:DWORD dst_unused:UNUSED_PAD src0_sel:WORD_1
	v_cvt_f32_f16_e32 v32, v144
	v_cvt_f32_f16_sdwa v37, v145 dst_sel:DWORD dst_unused:UNUSED_PAD src0_sel:WORD_1
	v_cvt_f32_f16_sdwa v39, v143 dst_sel:DWORD dst_unused:UNUSED_PAD src0_sel:WORD_1
	v_cvt_f32_f16_e32 v38, v143
	v_cvt_f32_f16_e32 v36, v145
	v_fma_f32 v28, v28, v44, v34
	v_fma_f32 v29, v29, v45, v35
	v_ashrrev_i32_e32 v99, 31, v98
	v_fma_f32 v32, v24, v40, v32
	v_fma_f32 v33, v25, v41, v33
	v_cvt_pk_f16_f32 v24, v28, v29
	v_lshlrev_b64 v[28:29], 11, v[98:99]
	v_fma_f32 v30, v30, v46, v38
	v_fma_f32 v31, v31, v47, v39
	v_fma_f32 v26, v26, v42, v36
	v_fma_f32 v27, v27, v43, v37
	v_lshl_add_u64 v[28:29], s[6:7], 0, v[28:29]
	v_cvt_pk_f16_f32 v27, v26, v27
	v_cvt_pk_f16_f32 v25, v30, v31
	v_cvt_pk_f16_f32 v26, v32, v33
	v_lshl_add_u64 v[28:29], v[28:29], 0, v[90:91]
	global_store_dwordx4 v[28:29], v[24:27], off
	v_cvt_f32_f16_sdwa v29, v130 dst_sel:DWORD dst_unused:UNUSED_PAD src0_sel:WORD_1
	v_cvt_f32_f16_e32 v28, v130
	v_cvt_f32_f16_sdwa v27, v132 dst_sel:DWORD dst_unused:UNUSED_PAD src0_sel:WORD_1
	v_cvt_f32_f16_e32 v26, v132
	v_cvt_f32_f16_sdwa v31, v133 dst_sel:DWORD dst_unused:UNUSED_PAD src0_sel:WORD_1
	v_cvt_f32_f16_sdwa v33, v131 dst_sel:DWORD dst_unused:UNUSED_PAD src0_sel:WORD_1
	v_cvt_f32_f16_e32 v32, v131
	v_cvt_f32_f16_e32 v30, v133
	v_add_u32_e32 v24, 0x90, v80
	v_fma_f32 v20, v20, v44, v28
	v_fma_f32 v21, v21, v45, v29
	v_ashrrev_i32_e32 v25, 31, v24
	v_fma_f32 v26, v16, v40, v26
	v_fma_f32 v27, v17, v41, v27
	v_cvt_pk_f16_f32 v16, v20, v21
	v_lshlrev_b64 v[20:21], 11, v[24:25]
	v_fma_f32 v22, v22, v46, v32
	v_fma_f32 v23, v23, v47, v33
	v_fma_f32 v18, v18, v42, v30
	v_fma_f32 v19, v19, v43, v31
	v_lshl_add_u64 v[20:21], s[6:7], 0, v[20:21]
	v_cvt_pk_f16_f32 v19, v18, v19
	v_cvt_pk_f16_f32 v17, v22, v23
	v_cvt_pk_f16_f32 v18, v26, v27
	v_lshl_add_u64 v[20:21], v[20:21], 0, v[90:91]
	global_store_dwordx4 v[20:21], v[16:19], off
	v_cvt_f32_f16_sdwa v21, v126 dst_sel:DWORD dst_unused:UNUSED_PAD src0_sel:WORD_1
	v_cvt_f32_f16_e32 v20, v126
	v_cvt_f32_f16_sdwa v19, v128 dst_sel:DWORD dst_unused:UNUSED_PAD src0_sel:WORD_1
	v_cvt_f32_f16_e32 v18, v128
	v_cvt_f32_f16_sdwa v23, v129 dst_sel:DWORD dst_unused:UNUSED_PAD src0_sel:WORD_1
	v_cvt_f32_f16_sdwa v25, v127 dst_sel:DWORD dst_unused:UNUSED_PAD src0_sel:WORD_1
	v_cvt_f32_f16_e32 v24, v127
	v_cvt_f32_f16_e32 v22, v129
	v_add_u32_e32 v16, 0xa0, v80
	v_fma_f32 v12, v12, v44, v20
	v_fma_f32 v13, v13, v45, v21
	v_ashrrev_i32_e32 v17, 31, v16
	v_fma_f32 v18, v8, v40, v18
	v_fma_f32 v19, v9, v41, v19
	v_cvt_pk_f16_f32 v8, v12, v13
	v_lshlrev_b64 v[12:13], 11, v[16:17]
	v_fma_f32 v14, v14, v46, v24
	v_fma_f32 v15, v15, v47, v25
	v_fma_f32 v10, v10, v42, v22
	v_fma_f32 v11, v11, v43, v23
	v_lshl_add_u64 v[12:13], s[6:7], 0, v[12:13]
	v_cvt_pk_f16_f32 v11, v10, v11
	v_cvt_pk_f16_f32 v9, v14, v15
	v_cvt_pk_f16_f32 v10, v18, v19
	v_lshl_add_u64 v[12:13], v[12:13], 0, v[90:91]
	global_store_dwordx4 v[12:13], v[8:11], off
	v_cvt_f32_f16_sdwa v13, v114 dst_sel:DWORD dst_unused:UNUSED_PAD src0_sel:WORD_1
	v_cvt_f32_f16_e32 v12, v114
	v_cvt_f32_f16_sdwa v11, v116 dst_sel:DWORD dst_unused:UNUSED_PAD src0_sel:WORD_1
	v_cvt_f32_f16_e32 v10, v116
	v_cvt_f32_f16_sdwa v15, v117 dst_sel:DWORD dst_unused:UNUSED_PAD src0_sel:WORD_1
	v_cvt_f32_f16_sdwa v17, v115 dst_sel:DWORD dst_unused:UNUSED_PAD src0_sel:WORD_1
	v_cvt_f32_f16_e32 v16, v115
	v_cvt_f32_f16_e32 v14, v117
	v_add_u32_e32 v8, 0xb0, v80
	v_fma_f32 v4, v4, v44, v12
	v_fma_f32 v5, v5, v45, v13
	v_ashrrev_i32_e32 v9, 31, v8
	v_fma_f32 v10, v0, v40, v10
	v_fma_f32 v11, v1, v41, v11
	v_cvt_pk_f16_f32 v0, v4, v5
	v_lshlrev_b64 v[4:5], 11, v[8:9]
	v_fma_f32 v6, v6, v46, v16
	v_fma_f32 v7, v7, v47, v17
	v_fma_f32 v2, v2, v42, v14
	v_fma_f32 v3, v3, v43, v15
	v_lshl_add_u64 v[4:5], s[6:7], 0, v[4:5]
	v_cvt_pk_f16_f32 v3, v2, v3
	v_cvt_pk_f16_f32 v1, v6, v7
	v_cvt_pk_f16_f32 v2, v10, v11
	v_lshl_add_u64 v[4:5], v[4:5], 0, v[90:91]
	global_store_dwordx4 v[4:5], v[0:3], off
	s_andn2_b64 vcc, exec, s[42:43]
	s_mov_b64 s[36:37], -1
	s_cbranch_vccnz .LBB0_597

.LBB0_654:
	s_lshl_b32 s7, s66, 2
	s_or_b32 s38, s7, s64
	s_ashr_i32 s25, s24, 31
	s_ashr_i32 s39, s38, 31
	s_lshl_b64 s[24:25], s[24:25], 21
	s_lshl_b64 s[38:39], s[38:39], 15
	s_add_u32 s7, s55, s24
	s_addc_u32 s9, s56, s25
	v_max_f32_e32 v122, 0, v122
	v_max_f32_e32 v123, 0, v123
	s_add_u32 s24, s7, s38
	v_mul_f32_e32 v162, v122, v122
	v_mul_f32_e32 v163, v123, v123
	s_addc_u32 s25, s9, s39
	v_max_f32_e32 v124, 0, v124
	v_lshl_add_u64 v[160:161], s[24:25], 0, v[138:139]
	v_max_f32_e32 v126, 0, v126
	v_max_f32_e32 v127, 0, v127
	v_max_f32_e32 v122, 0, v128
	v_max_f32_e32 v123, 0, v129
	v_max_f32_e32 v125, 0, v125
	v_lshl_add_u64 v[160:161], v[160:161], 0, s[10:11]
	v_mul_f32_e32 v126, v126, v126
	v_mul_f32_e32 v127, v127, v127
	v_mul_f32_e32 v128, v122, v122
	v_mul_f32_e32 v129, v123, v123
	v_mul_f32_e32 v164, v124, v124
	v_mul_f32_e32 v165, v125, v125
	v_lshl_add_u64 v[160:161], v[160:161], 0, v[80:81]
	v_cvt_pk_bf16_f32 v122, v126, v127
	v_cvt_pk_bf16_f32 v123, v128, v129
	v_cvt_pk_bf16_f32 v124, v162, v163
	v_cvt_pk_bf16_f32 v125, v164, v165
	v_max_f32_e32 v114, 0, v114
	v_max_f32_e32 v115, 0, v115
	global_store_dwordx4 v[160:161], v[122:125], off
	s_nop 1
	v_mul_f32_e32 v122, v114, v114
	v_mul_f32_e32 v123, v115, v115
	v_max_f32_e32 v118, 0, v118
	v_max_f32_e32 v119, 0, v119
	v_max_f32_e32 v116, 0, v116
	v_mul_f32_e32 v118, v118, v118
	v_mul_f32_e32 v119, v119, v119
	v_max_f32_e32 v114, 0, v120
	v_max_f32_e32 v115, 0, v121
	v_max_f32_e32 v117, 0, v117
	v_mul_f32_e32 v120, v114, v114
	v_mul_f32_e32 v121, v115, v115
	v_mul_f32_e32 v124, v116, v116
	v_mul_f32_e32 v125, v117, v117
	v_cvt_pk_bf16_f32 v114, v118, v119
	v_add_co_u32_e32 v118, vcc, s93, v160
	v_cvt_pk_bf16_f32 v115, v120, v121
	v_cvt_pk_bf16_f32 v116, v122, v123
	v_cvt_pk_bf16_f32 v117, v124, v125
	v_addc_co_u32_e32 v119, vcc, 0, v161, vcc
	v_max_f32_e32 v106, 0, v106
	v_max_f32_e32 v107, 0, v107
	global_store_dwordx4 v[118:119], v[114:117], off
	s_nop 1
	v_mul_f32_e32 v116, v106, v106
	v_mul_f32_e32 v117, v107, v107
	v_max_f32_e32 v108, 0, v108
	v_lshl_add_u64 v[114:115], s[24:25], 0, v[140:141]
	v_max_f32_e32 v110, 0, v110
	v_max_f32_e32 v111, 0, v111
	v_max_f32_e32 v106, 0, v112
	v_max_f32_e32 v107, 0, v113
	v_max_f32_e32 v109, 0, v109
	v_lshl_add_u64 v[114:115], v[114:115], 0, s[10:11]
	v_mul_f32_e32 v110, v110, v110
	v_mul_f32_e32 v111, v111, v111
	v_mul_f32_e32 v112, v106, v106
	v_mul_f32_e32 v113, v107, v107
	v_mul_f32_e32 v118, v108, v108
	v_mul_f32_e32 v119, v109, v109
	v_lshl_add_u64 v[114:115], v[114:115], 0, v[80:81]
	v_cvt_pk_bf16_f32 v106, v110, v111
	v_cvt_pk_bf16_f32 v107, v112, v113
	v_cvt_pk_bf16_f32 v108, v116, v117
	v_cvt_pk_bf16_f32 v109, v118, v119
	v_max_f32_e32 v98, 0, v98
	v_max_f32_e32 v99, 0, v99
	global_store_dwordx4 v[114:115], v[106:109], off
	s_nop 1
	v_mul_f32_e32 v106, v98, v98
	v_mul_f32_e32 v107, v99, v99
	v_max_f32_e32 v102, 0, v102
	v_max_f32_e32 v103, 0, v103
	v_max_f32_e32 v100, 0, v100
	v_mul_f32_e32 v102, v102, v102
	v_mul_f32_e32 v103, v103, v103
	v_max_f32_e32 v98, 0, v104
	v_max_f32_e32 v99, 0, v105
	v_max_f32_e32 v101, 0, v101
	v_mul_f32_e32 v104, v98, v98
	v_mul_f32_e32 v105, v99, v99
	v_mul_f32_e32 v108, v100, v100
	v_mul_f32_e32 v109, v101, v101
	v_cvt_pk_bf16_f32 v98, v102, v103
	v_add_co_u32_e32 v102, vcc, s93, v114
	v_cvt_pk_bf16_f32 v99, v104, v105
	v_cvt_pk_bf16_f32 v100, v106, v107
	v_cvt_pk_bf16_f32 v101, v108, v109
	v_addc_co_u32_e32 v103, vcc, 0, v115, vcc
	v_max_f32_e32 v90, 0, v90
	v_max_f32_e32 v91, 0, v91
	global_store_dwordx4 v[102:103], v[98:101], off
	s_nop 1
	v_mul_f32_e32 v100, v90, v90
	v_mul_f32_e32 v101, v91, v91
	v_max_f32_e32 v92, 0, v92
	v_lshl_add_u64 v[98:99], s[24:25], 0, v[142:143]
	v_max_f32_e32 v94, 0, v94
	v_max_f32_e32 v95, 0, v95
	v_max_f32_e32 v90, 0, v96
	v_max_f32_e32 v91, 0, v97
	v_max_f32_e32 v93, 0, v93
	v_lshl_add_u64 v[98:99], v[98:99], 0, s[10:11]
	v_mul_f32_e32 v94, v94, v94
	v_mul_f32_e32 v95, v95, v95
	v_mul_f32_e32 v96, v90, v90
	v_mul_f32_e32 v97, v91, v91
	v_mul_f32_e32 v102, v92, v92
	v_mul_f32_e32 v103, v93, v93
	v_lshl_add_u64 v[98:99], v[98:99], 0, v[80:81]
	v_cvt_pk_bf16_f32 v90, v94, v95
	v_cvt_pk_bf16_f32 v91, v96, v97
	v_cvt_pk_bf16_f32 v92, v100, v101
	v_cvt_pk_bf16_f32 v93, v102, v103
	v_max_f32_e32 v82, 0, v82
	v_max_f32_e32 v83, 0, v83
	global_store_dwordx4 v[98:99], v[90:93], off
	s_nop 1
	v_mul_f32_e32 v90, v82, v82
	v_mul_f32_e32 v91, v83, v83
	v_max_f32_e32 v86, 0, v86
	v_max_f32_e32 v87, 0, v87
	v_max_f32_e32 v84, 0, v84
	v_mul_f32_e32 v86, v86, v86
	v_mul_f32_e32 v87, v87, v87
	v_max_f32_e32 v82, 0, v88
	v_max_f32_e32 v83, 0, v89
	v_max_f32_e32 v85, 0, v85
	v_mul_f32_e32 v88, v82, v82
	v_mul_f32_e32 v89, v83, v83
	v_mul_f32_e32 v92, v84, v84
	v_mul_f32_e32 v93, v85, v85
	v_cvt_pk_bf16_f32 v82, v86, v87
	v_add_co_u32_e32 v86, vcc, s93, v98
	v_cvt_pk_bf16_f32 v83, v88, v89
	v_cvt_pk_bf16_f32 v84, v90, v91
	v_cvt_pk_bf16_f32 v85, v92, v93
	v_addc_co_u32_e32 v87, vcc, 0, v99, vcc
	v_max_f32_e32 v72, 0, v72
	v_max_f32_e32 v73, 0, v73
	global_store_dwordx4 v[86:87], v[82:85], off
	s_nop 1
	v_mul_f32_e32 v84, v72, v72
	v_mul_f32_e32 v85, v73, v73
	v_max_f32_e32 v74, 0, v74
	v_lshl_add_u64 v[82:83], s[24:25], 0, v[144:145]
	v_max_f32_e32 v76, 0, v76
	v_max_f32_e32 v77, 0, v77
	v_max_f32_e32 v72, 0, v78
	v_max_f32_e32 v73, 0, v79
	v_max_f32_e32 v75, 0, v75
	v_lshl_add_u64 v[82:83], v[82:83], 0, s[10:11]
	v_mul_f32_e32 v76, v76, v76
	v_mul_f32_e32 v77, v77, v77
	v_mul_f32_e32 v78, v72, v72
	v_mul_f32_e32 v79, v73, v73
	v_mul_f32_e32 v86, v74, v74
	v_mul_f32_e32 v87, v75, v75
	v_lshl_add_u64 v[82:83], v[82:83], 0, v[80:81]
	v_cvt_pk_bf16_f32 v72, v76, v77
	v_cvt_pk_bf16_f32 v73, v78, v79
	v_cvt_pk_bf16_f32 v74, v84, v85
	v_cvt_pk_bf16_f32 v75, v86, v87
	v_max_f32_e32 v64, 0, v64
	v_max_f32_e32 v65, 0, v65
	global_store_dwordx4 v[82:83], v[72:75], off
	s_nop 1
	v_mul_f32_e32 v72, v64, v64
	v_mul_f32_e32 v73, v65, v65
	v_max_f32_e32 v68, 0, v68
	v_max_f32_e32 v69, 0, v69
	v_max_f32_e32 v66, 0, v66
	v_mul_f32_e32 v68, v68, v68
	v_mul_f32_e32 v69, v69, v69
	v_max_f32_e32 v64, 0, v70
	v_max_f32_e32 v65, 0, v71
	v_max_f32_e32 v67, 0, v67
	v_mul_f32_e32 v70, v64, v64
	v_mul_f32_e32 v71, v65, v65
	v_mul_f32_e32 v74, v66, v66
	v_mul_f32_e32 v75, v67, v67
	v_cvt_pk_bf16_f32 v64, v68, v69
	v_add_co_u32_e32 v68, vcc, s93, v82
	v_cvt_pk_bf16_f32 v65, v70, v71
	v_cvt_pk_bf16_f32 v66, v72, v73
	v_cvt_pk_bf16_f32 v67, v74, v75
	v_addc_co_u32_e32 v69, vcc, 0, v83, vcc
	v_max_f32_e32 v56, 0, v56
	v_max_f32_e32 v57, 0, v57
	global_store_dwordx4 v[68:69], v[64:67], off
	s_nop 1
	v_mul_f32_e32 v66, v56, v56
	v_mul_f32_e32 v67, v57, v57
	v_max_f32_e32 v58, 0, v58
	v_lshl_add_u64 v[64:65], s[24:25], 0, v[146:147]
	v_max_f32_e32 v60, 0, v60
	v_max_f32_e32 v61, 0, v61
	v_max_f32_e32 v56, 0, v62
	v_max_f32_e32 v57, 0, v63
	v_max_f32_e32 v59, 0, v59
	v_lshl_add_u64 v[64:65], v[64:65], 0, s[10:11]
	v_mul_f32_e32 v60, v60, v60
	v_mul_f32_e32 v61, v61, v61
	v_mul_f32_e32 v62, v56, v56
	v_mul_f32_e32 v63, v57, v57
	v_mul_f32_e32 v68, v58, v58
	v_mul_f32_e32 v69, v59, v59
	v_lshl_add_u64 v[64:65], v[64:65], 0, v[80:81]
	v_cvt_pk_bf16_f32 v56, v60, v61
	v_cvt_pk_bf16_f32 v57, v62, v63
	v_cvt_pk_bf16_f32 v58, v66, v67
	v_cvt_pk_bf16_f32 v59, v68, v69
	v_max_f32_e32 v48, 0, v48
	v_max_f32_e32 v49, 0, v49
	global_store_dwordx4 v[64:65], v[56:59], off
	s_nop 1
	v_mul_f32_e32 v56, v48, v48
	v_mul_f32_e32 v57, v49, v49
	v_max_f32_e32 v52, 0, v52
	v_max_f32_e32 v53, 0, v53
	v_max_f32_e32 v50, 0, v50
	v_mul_f32_e32 v52, v52, v52
	v_mul_f32_e32 v53, v53, v53
	v_max_f32_e32 v48, 0, v54
	v_max_f32_e32 v49, 0, v55
	v_max_f32_e32 v51, 0, v51
	v_mul_f32_e32 v54, v48, v48
	v_mul_f32_e32 v55, v49, v49
	v_mul_f32_e32 v58, v50, v50
	v_mul_f32_e32 v59, v51, v51
	v_cvt_pk_bf16_f32 v48, v52, v53
	v_add_co_u32_e32 v52, vcc, s93, v64
	v_cvt_pk_bf16_f32 v49, v54, v55
	v_cvt_pk_bf16_f32 v50, v56, v57
	v_cvt_pk_bf16_f32 v51, v58, v59
	v_addc_co_u32_e32 v53, vcc, 0, v65, vcc
	v_max_f32_e32 v40, 0, v40
	v_max_f32_e32 v41, 0, v41
	global_store_dwordx4 v[52:53], v[48:51], off
	s_nop 1
	v_mul_f32_e32 v50, v40, v40
	v_mul_f32_e32 v51, v41, v41
	v_max_f32_e32 v42, 0, v42
	v_lshl_add_u64 v[48:49], s[24:25], 0, v[148:149]
	v_max_f32_e32 v44, 0, v44
	v_max_f32_e32 v45, 0, v45
	v_max_f32_e32 v40, 0, v46
	v_max_f32_e32 v41, 0, v47
	v_max_f32_e32 v43, 0, v43
	v_lshl_add_u64 v[48:49], v[48:49], 0, s[10:11]
	v_mul_f32_e32 v44, v44, v44
	v_mul_f32_e32 v45, v45, v45
	v_mul_f32_e32 v46, v40, v40
	v_mul_f32_e32 v47, v41, v41
	v_mul_f32_e32 v52, v42, v42
	v_mul_f32_e32 v53, v43, v43
	v_lshl_add_u64 v[48:49], v[48:49], 0, v[80:81]
	v_cvt_pk_bf16_f32 v40, v44, v45
	v_cvt_pk_bf16_f32 v41, v46, v47
	v_cvt_pk_bf16_f32 v42, v50, v51
	v_cvt_pk_bf16_f32 v43, v52, v53
	v_max_f32_e32 v32, 0, v32
	v_max_f32_e32 v33, 0, v33
	global_store_dwordx4 v[48:49], v[40:43], off
	s_nop 1
	v_mul_f32_e32 v40, v32, v32
	v_mul_f32_e32 v41, v33, v33
	v_max_f32_e32 v36, 0, v36
	v_max_f32_e32 v37, 0, v37
	v_max_f32_e32 v34, 0, v34
	v_mul_f32_e32 v36, v36, v36
	v_mul_f32_e32 v37, v37, v37
	v_max_f32_e32 v32, 0, v38
	v_max_f32_e32 v33, 0, v39
	v_max_f32_e32 v35, 0, v35
	v_mul_f32_e32 v38, v32, v32
	v_mul_f32_e32 v39, v33, v33
	v_mul_f32_e32 v42, v34, v34
	v_mul_f32_e32 v43, v35, v35
	v_cvt_pk_bf16_f32 v32, v36, v37
	v_add_co_u32_e32 v36, vcc, s93, v48
	v_cvt_pk_bf16_f32 v33, v38, v39
	v_cvt_pk_bf16_f32 v34, v40, v41
	v_cvt_pk_bf16_f32 v35, v42, v43
	v_addc_co_u32_e32 v37, vcc, 0, v49, vcc
	v_max_f32_e32 v24, 0, v24
	v_max_f32_e32 v25, 0, v25
	global_store_dwordx4 v[36:37], v[32:35], off
	s_nop 1
	v_mul_f32_e32 v34, v24, v24
	v_mul_f32_e32 v35, v25, v25
	v_max_f32_e32 v26, 0, v26
	v_lshl_add_u64 v[32:33], s[24:25], 0, v[150:151]
	v_max_f32_e32 v28, 0, v28
	v_max_f32_e32 v29, 0, v29
	v_max_f32_e32 v24, 0, v30
	v_max_f32_e32 v25, 0, v31
	v_max_f32_e32 v27, 0, v27
	v_lshl_add_u64 v[32:33], v[32:33], 0, s[10:11]
	v_mul_f32_e32 v28, v28, v28
	v_mul_f32_e32 v29, v29, v29
	v_mul_f32_e32 v30, v24, v24
	v_mul_f32_e32 v31, v25, v25
	v_mul_f32_e32 v36, v26, v26
	v_mul_f32_e32 v37, v27, v27
	v_lshl_add_u64 v[32:33], v[32:33], 0, v[80:81]
	v_cvt_pk_bf16_f32 v24, v28, v29
	v_cvt_pk_bf16_f32 v25, v30, v31
	v_cvt_pk_bf16_f32 v26, v34, v35
	v_cvt_pk_bf16_f32 v27, v36, v37
	v_max_f32_e32 v16, 0, v16
	v_max_f32_e32 v17, 0, v17
	global_store_dwordx4 v[32:33], v[24:27], off
	s_nop 1
	v_mul_f32_e32 v24, v16, v16
	v_mul_f32_e32 v25, v17, v17
	v_max_f32_e32 v20, 0, v20
	v_max_f32_e32 v21, 0, v21
	v_max_f32_e32 v18, 0, v18
	v_mul_f32_e32 v20, v20, v20
	v_mul_f32_e32 v21, v21, v21
	v_max_f32_e32 v16, 0, v22
	v_max_f32_e32 v17, 0, v23
	v_max_f32_e32 v19, 0, v19
	v_mul_f32_e32 v22, v16, v16
	v_mul_f32_e32 v23, v17, v17
	v_mul_f32_e32 v26, v18, v18
	v_mul_f32_e32 v27, v19, v19
	v_cvt_pk_bf16_f32 v16, v20, v21
	v_add_co_u32_e32 v20, vcc, s93, v32
	v_cvt_pk_bf16_f32 v17, v22, v23
	v_cvt_pk_bf16_f32 v18, v24, v25
	v_cvt_pk_bf16_f32 v19, v26, v27
	v_addc_co_u32_e32 v21, vcc, 0, v33, vcc
	v_max_f32_e32 v8, 0, v8
	v_max_f32_e32 v9, 0, v9
	global_store_dwordx4 v[20:21], v[16:19], off
	s_nop 1
	v_mul_f32_e32 v18, v8, v8
	v_mul_f32_e32 v19, v9, v9
	v_max_f32_e32 v10, 0, v10
	v_lshl_add_u64 v[16:17], s[24:25], 0, v[152:153]
	v_max_f32_e32 v12, 0, v12
	v_max_f32_e32 v13, 0, v13
	v_max_f32_e32 v8, 0, v14
	v_max_f32_e32 v9, 0, v15
	v_max_f32_e32 v11, 0, v11
	v_lshl_add_u64 v[16:17], v[16:17], 0, s[10:11]
	v_mul_f32_e32 v12, v12, v12
	v_mul_f32_e32 v13, v13, v13
	v_mul_f32_e32 v14, v8, v8
	v_mul_f32_e32 v15, v9, v9
	v_mul_f32_e32 v20, v10, v10
	v_mul_f32_e32 v21, v11, v11
	v_lshl_add_u64 v[16:17], v[16:17], 0, v[80:81]
	v_cvt_pk_bf16_f32 v8, v12, v13
	v_cvt_pk_bf16_f32 v9, v14, v15
	v_cvt_pk_bf16_f32 v10, v18, v19
	v_cvt_pk_bf16_f32 v11, v20, v21
	v_max_f32_e32 v0, 0, v0
	v_max_f32_e32 v1, 0, v1
	global_store_dwordx4 v[16:17], v[8:11], off
	s_nop 1
	v_mul_f32_e32 v8, v0, v0
	v_mul_f32_e32 v9, v1, v1
	v_max_f32_e32 v4, 0, v4
	v_max_f32_e32 v5, 0, v5
	v_max_f32_e32 v2, 0, v2
	v_mul_f32_e32 v4, v4, v4
	v_mul_f32_e32 v5, v5, v5
	v_max_f32_e32 v0, 0, v6
	v_max_f32_e32 v1, 0, v7
	v_max_f32_e32 v3, 0, v3
	v_mul_f32_e32 v6, v0, v0
	v_mul_f32_e32 v7, v1, v1
	v_cvt_pk_bf16_f32 v0, v4, v5
	v_add_co_u32_e32 v4, vcc, 0x10000, v16
	v_mul_f32_e32 v10, v2, v2
	v_mul_f32_e32 v11, v3, v3
	s_nop 0
	v_addc_co_u32_e32 v5, vcc, 0, v17, vcc
	v_cvt_pk_bf16_f32 v1, v6, v7
	v_cvt_pk_bf16_f32 v2, v8, v9
	v_cvt_pk_bf16_f32 v3, v10, v11
	s_andn2_b64 vcc, exec, s[36:37]
	s_mov_b64 s[24:25], -1
	s_movk_i32 s72, 0x1fff
	s_mov_b64 s[74:75], 0x1000
	global_store_dwordx4 v[4:5], v[0:3], off
	s_cbranch_vccnz .LBB0_647
	s_andn2_b64 vcc, exec, s[2:3]
	s_cbranch_vccnz .LBB0_646
	s_barrier
	s_branch .LBB0_646
